# v26 plus one static s_setprio 1 for waves 0-3 during the attention phase (reset after)
# baseline (speedup 1.0000x reference)
.LBB0_1005:
	s_cmp_gt_u32 s77, 3
	s_cbranch_scc1 .Lattn_noprio
	s_setprio 1

.LBB0_1157:
	s_setprio 0
	s_waitcnt vmcnt(0)
	v_readfirstlane_b32 s0, v194
	v_readlane_b32 s62, v241, 5
	s_cmp_gt_u32 s0, 63
	v_readlane_b32 s63, v241, 6
	s_waitcnt lgkmcnt(0)
	s_barrier
	s_cbranch_scc1 .LBB0_1211
	v_mbcnt_lo_u32_b32 v0, -1, 0
	v_mbcnt_hi_u32_b32 v0, -1, v0
	s_nop 0
	v_cmp_eq_u32_e32 vcc, 0, v0
	s_and_saveexec_b64 s[0:1], vcc
	s_cbranch_execz .LBB0_1210
	v_mov_b32_e32 v20, 0x23ff0
	s_waitcnt vmcnt(0) lgkmcnt(0)
	ds_read_b128 v[20:23], v20
	s_waitcnt lgkmcnt(0)
	v_readfirstlane_b32 s3, v22
	s_nop 0
	s_cmp_eq_u32 s3, 0
	s_cbranch_scc1 .Lfb_slow_4
	v_add_u32_e32 v23, 1, v23
	v_mov_b32_e32 v24, 0x23ffc
	ds_write_b32 v24, v23
	v_mul_lo_u32 v25, v23, v20
	s_getreg_b32 s3, hwreg(HW_REG_XCC_ID, 0, 4)
	s_and_b32 s3, s3, 7
	s_lshl_b32 s3, s3, 8
	s_add_u32 s3, s3, 0x3680
	s_add_u32 s4, s92, 0x510000
	s_addc_u32 s5, s93, 0
	v_mov_b32_e32 v26, s3
	v_mov_b32_e32 v27, 1
	global_atomic_add v26, v27, s[4:5]
	s_mov_b32 s8, 0
